# speedup vs baseline: 1.0065x; 1.0065x over previous
;     __device__ __forceinline__ bf16_t* Ksf() const { return (bf16_t*)(ws + OFF_Ksf); }
; DEV void st_bf4(bf16_t* p, float a, float b, float c, float d) { uint2 w; w.x = pk_bf16(a, b); w.y = pk_bf16(c, d); *(uint2*)p = w; }
; DEV void cache_convert(const Params& p, int l, int vb, int vnb, float* sm) {
;     ...
;     for (int i = gt; i < 8 * PAST * 96; i += gn) {
;         const int b = i / (PAST * 96), rem = i % (PAST * 96);
;         const float4 v = *(const float4*)(p.cache_fox_k + ((size_t)(l * 8 + b) * PAST * 384) + (size_t)rem * 4);
;         st_bf4(p.Ksf() + (size_t)b * KSP * 384 + (size_t)rem * 4, v.x, v.y, v.z, v.w);
;     }
.LBB0_2711:
	v_mul_hi_i32 v2, v1, s13
	v_lshrrev_b32_e32 v3, 31, v2
	v_ashrrev_i32_e32 v2, 15, v2
	v_add_u32_e32 v10, v2, v3
	v_mul_i32_i24_e32 v2, 0x30000, v10
	v_add_u32_e32 v4, s9, v10
	v_sub_u32_e32 v6, v1, v2
	v_mul_hi_i32_i24_e32 v3, 0x300000, v4
	v_mul_i32_i24_e32 v2, 0x300000, v4
	v_lshl_add_u64 v[2:3], s[70:71], 0, v[2:3]
	v_ashrrev_i32_e32 v7, 31, v6
	v_lshl_add_u64 v[2:3], v[6:7], 4, v[2:3]
	flat_load_dwordx4 v[2:5], v[2:3]
	v_mov_b64_e32 v[8:9], s[2:3]
	v_mul_i32_i24_e32 v10, 0x840, v10
	v_mad_i64_i32 v[8:9], s[10:11], v10, s12, v[8:9]
	v_add_u32_e32 v1, s8, v1
	s_mov_b32 s10, 0x17ffff
	v_cmp_lt_i32_e32 vcc, s10, v1
	v_lshl_add_u64 v[6:7], v[6:7], 3, v[8:9]
	s_or_b64 s[4:5], vcc, s[4:5]
	s_waitcnt vmcnt(0) lgkmcnt(0)
	v_cvt_pk_bf16_f32 v2, v2, v3
	v_cvt_pk_bf16_f32 v3, v4, v5
	flat_store_dwordx2 v[6:7], v[2:3]
	s_andn2_b64 exec, exec, s[4:5]
	s_cbranch_execnz .LBB0_2711

;     __device__ __forceinline__ bf16_t* Ksb() const { return (bf16_t*)(ws + OFF_Ksb); }
; DEV void st_bf4(bf16_t* p, float a, float b, float c, float d) { uint2 w; w.x = pk_bf16(a, b); w.y = pk_bf16(c, d); *(uint2*)p = w; }
; DEV void cache_convert(const Params& p, int l, int vb, int vnb, float* sm) {
;     ...
;     for (int i = gt; i < 8 * PAST * 64; i += gn) {
;         const int b = i / (PAST * 64), rem = i % (PAST * 64);
;         const float4 v = *(const float4*)(p.cache_sb_k + ((size_t)(l * 8 + b) * PAST * 256) + (size_t)rem * 4);
;         st_bf4(p.Ksb() + (size_t)b * KSP * 256 + (size_t)rem * 4, v.x, v.y, v.z, v.w);
;     }
.LBB0_2714:
	v_ashrrev_i32_e32 v2, 31, v1
	v_lshrrev_b32_e32 v2, 15, v2
	v_add_u32_e32 v2, v1, v2
	v_ashrrev_i32_e32 v8, 17, v2
	v_mul_i32_i24_e32 v3, 0x20000, v8
	v_add_u32_e32 v2, s9, v8
	v_sub_u32_e32 v6, v1, v3
	v_ashrrev_i32_e32 v3, 31, v2
	v_lshlrev_b64 v[2:3], 21, v[2:3]
	v_ashrrev_i32_e32 v7, 31, v6
	v_lshl_add_u64 v[2:3], s[96:97], 0, v[2:3]
	v_lshl_add_u64 v[2:3], v[6:7], 4, v[2:3]
	flat_load_dwordx4 v[2:5], v[2:3]
	v_mul_i32_i24_e32 v8, 0x840, v8
	v_ashrrev_i32_e32 v9, 31, v8
	v_add_u32_e32 v1, s8, v1
	v_lshlrev_b64 v[8:9], 9, v[8:9]
	s_mov_b32 s10, 0xfffff
	v_cmp_lt_i32_e32 vcc, s10, v1
	v_lshl_add_u64 v[8:9], s[2:3], 0, v[8:9]
	s_or_b64 s[4:5], vcc, s[4:5]
	v_lshl_add_u64 v[6:7], v[6:7], 3, v[8:9]
	s_waitcnt vmcnt(0) lgkmcnt(0)
	v_cvt_pk_bf16_f32 v2, v2, v3
	v_cvt_pk_bf16_f32 v3, v4, v5
	flat_store_dwordx2 v[6:7], v[2:3]
	s_andn2_b64 exec, exec, s[4:5]
	s_cbranch_execnz .LBB0_2714
